# HGRN2 decay chain prologue: both partial-sum LDS reads issued up front (one LDS round trip before the row-group prefix instead of two)
# baseline (speedup 1.0000x reference)
; #define LAS __attribute__((address_space(3)))
; #define GAS __attribute__((address_space(1)))
; __device__ __forceinline__ bf16_t f2bf(float x) { return (bf16_t)(cvt_pk_bf16(x, x) & 0xffffu); }
; __device__ __forceinline__ float bf2f(bf16_t v) { return __uint_as_float((unsigned)v << 16); }
; template <int DK, int DVS, bool RET> ...
;     ...
;                 for (int j = 0; j < 4; ++j) STB[(tv * 16 + quad * 4 + j) * LK + (kt0 + t) * 16 + l16] = f2bf(st[t][j]);
;             { const int p = tid >> 3, vg = tid & 7; const long row = R0 + (dir ? 63 - p : p); vraw = *(const GAS vvec_t*)(Vg + row * ldv + vcol0 + vg * VPT); }
;             float bl;
;             if constexpr (RET) {
;                 static_assert(!RET || DK == 256, "retention prep: 64 x 256 = 2048 eight-wide items, four per thread");
;                 bl = 64.f * lg;
; #pragma unroll
;                 for (int j = 0; j < 4; ++j) { const int it = tid + 512 * j, p = it & 63, k0 = (it >> 6) * 8; const float bb = (float)(p + 1) * lg;
;                     const float eq = __expf(bb), ek = __expf(-bb); float a[8], c[8];
; #pragma unroll
;                     for (int e = 0; e < 8; ++e) { a[e] = bf2f((bf16_t)qv[j][e]) * eq; c[e] = bf2f((bf16_t)kv[j][e]) * ek; }
;                     *(LAS u32x4*)(QD + p * LK + k0) = pack8(a); *(LAS u32x4*)(KD + p * LK + k0) = pack8(c); }
;             } else {
;                 float c = 0.f;
; #pragma unroll
;                 for (int i = 0; i < PPT; ++i) c += lc[i];
;                 TOT[pg * 128 + kx] = c;
;                 GLA_BAR();
;                 float off = 0.f; bl = 0.f;
; #pragma unroll
;                 for (int g = 0; g < NPG; ++g) { const float t = TOT[g * 128 + kx]; if (g < pg) off += t; bl += t; }
;                 float bb = off;
; #pragma unroll
;                 for (int i = 0; i < PPT; ++i) { const int p = pg * PPT + i;
;                     const float qf = bf2f(qr[i]), kf = 1.f - __expf(lc[i]); bb += lc[i];
;                     QD[p * LK + kx] = f2bf(qf * __expf(bb)); KD[p * LK + kx] = f2bf(kf * __expf(-bb)); }
;             }
;             if (pg == 0) EL[kx] = __expf(bl);
;             { const int p = tid >> 3, vg = tid & 7; *(LAS vvec_t*)(VI + p * LV + vg * VPT) = vraw; }
;         }
;         if (step + 1 < 68) GLA_LOAD(step + 1);
.LBB0_54:
	v_cvt_pk_bf16_f32 v71, v71, s0
	s_waitcnt lgkmcnt(0)
	s_barrier
	ds_write_b16 v213, v71 offset:272
	v_cvt_pk_bf16_f32 v71, v72, s0
	s_waitcnt vmcnt(0)
	v_add_f32_e32 v72, 0, v132
	v_add_f32_e32 v72, v134, v72
	v_add_f32_e32 v72, v136, v72
	v_add_f32_e32 v72, v138, v72
	v_add_f32_e32 v72, v140, v72
	s_cmp_gt_u32 s36, 3
	v_add_f32_e32 v72, v142, v72
	s_cselect_b32 s40, 0x47, 3
	v_add_f32_e32 v72, v147, v72
	s_add_i32 s40, s40, s41
	v_add_f32_e32 v72, v151, v72
	s_and_b64 s[44:45], s[30:31], exec
	v_add_f32_e32 v72, v210, v72
	s_cselect_b32 s40, s36, s40
	v_add_f32_e32 v72, v220, v72
	s_lshl_b32 s40, s40, 6
	ds_write_b16 v213, v71 offset:544
	v_cvt_pk_bf16_f32 v71, v73, s0
	v_add_f32_e32 v72, v222, v72
	s_ashr_i32 s45, s40, 31
	ds_write_b16 v213, v71 offset:816
	v_cvt_pk_bf16_f32 v71, v74, s0
	v_add_f32_e32 v72, v224, v72
	ds_write_b16 v214, v71
	v_cvt_pk_bf16_f32 v71, v75, s0
	s_add_u32 s44, s42, s40
	v_add_f32_e32 v72, v226, v72
	ds_write_b16 v214, v71 offset:272
	v_cvt_pk_bf16_f32 v71, v234, s0
	v_cvt_pk_bf16_f32 v70, v70, s0
	s_addc_u32 s45, s43, s45
	v_add_f32_e32 v72, v228, v72
	ds_write_b16 v214, v71 offset:544
	ds_write_b16 v214, v70 offset:816
	v_lshl_add_u64 v[70:71], s[44:45], 0, v[56:57]
	v_add_f32_e32 v72, v230, v72
	v_cvt_pk_bf16_f32 v110, v0, s0
	v_lshlrev_b64 v[70:71], 11, v[70:71]
	v_add_f32_e32 v72, v232, v72
	ds_write_b16 v213, v110
	v_lshl_add_u64 v[70:71], v[58:59], 0, v[70:71]
	ds_write_b32 v152, v72
	global_load_dwordx2 v[70:71], v[70:71], off
	s_waitcnt lgkmcnt(0)
	s_barrier
	s_add_i32 s39, s36, 1
	s_min_i32 s39, s39, 0x43
	s_cmp_gt_u32 s39, 3
	s_cselect_b32 s38, 0x47, 3
	s_sub_i32 s38, s38, s39
	s_and_b64 s[54:55], s[30:31], exec
	s_cselect_b32 s38, s39, s38
	s_lshl_b32 s38, s38, 6
	s_ashr_i32 s39, s38, 31
	s_add_u32 s54, s42, s38
	s_addc_u32 s55, s43, s39
	s_lshl_b64 s[38:39], s[54:55], 11
	s_add_u32 s38, s38, s90
	s_addc_u32 s39, s39, s91
	s_lshl_b64 s[54:55], s[54:55], 13
	s_add_u32 s54, s54, s64
	s_addc_u32 s55, s55, s65
	ds_read2st64_b32 v[72:73], v153 offset1:2
	ds_read2st64_b32 v[74:75], v153 offset0:4 offset1:6
	v_mul_f32_e32 v111, 0x3fb8aa3b, v132
	v_mul_f32_e32 v112, 0xbfb8aa3b, v132
	s_waitcnt lgkmcnt(0)
	v_add_f32_e32 v72, 0, v72
	v_cndmask_b32_e64 v113, 0, v72, s[6:7]
	v_add_f32_e32 v110, v73, v113
	v_cndmask_b32_e64 v110, v113, v110, s[8:9]
	v_add_f32_e32 v113, v74, v110
	v_cndmask_b32_e64 v110, v110, v113, s[10:11]
	v_add_f32_e32 v113, v75, v110
	v_cndmask_b32_e64 v110, v110, v113, s[12:13]
	v_mul_f32_e32 v113, 0xbfb8aa3b, v110
	v_mul_f32_e32 v110, 0x3fb8aa3b, v110
	v_exp_f32_e32 v113, v113
	v_exp_f32_e32 v110, v110
	global_load_dword v132, v20, s[54:55]
	v_exp_f32_e32 v111, v111
	v_exp_f32_e32 v112, v112
	v_mul_f32_e32 v110, v110, v111
	v_mul_f32_e32 v113, v113, v112
	v_sub_f32_e32 v111, 1.0, v111
	v_lshlrev_b32_e32 v112, 16, v133
	global_load_ushort v133, v21, s[38:39]
	v_mul_f32_e32 v111, v111, v113
	v_mul_f32_e32 v112, v110, v112
	v_cvt_pk_bf16_f32 v111, v111, s0
	v_cvt_pk_bf16_f32 v112, v112, s0
	ds_write_b16 v160, v112
	ds_write_b16 v161, v111
	v_mul_f32_e32 v111, 0x3fb8aa3b, v134
	v_mul_f32_e32 v112, 0xbfb8aa3b, v134
	global_load_dword v134, v26, s[54:55]
	v_exp_f32_e32 v111, v111
	v_exp_f32_e32 v112, v112
	v_mul_f32_e32 v110, v110, v111
	v_mul_f32_e32 v113, v113, v112
	v_sub_f32_e32 v111, 1.0, v111
	v_lshlrev_b32_e32 v112, 16, v135
	global_load_ushort v135, v27, s[38:39]
	v_mul_f32_e32 v111, v111, v113
	v_mul_f32_e32 v112, v110, v112
	v_cvt_pk_bf16_f32 v111, v111, s0
	v_cvt_pk_bf16_f32 v112, v112, s0
	ds_write_b16 v163, v112
	ds_write_b16 v164, v111
	v_mul_f32_e32 v111, 0x3fb8aa3b, v136
	v_mul_f32_e32 v112, 0xbfb8aa3b, v136
	global_load_dword v136, v28, s[54:55]
	v_exp_f32_e32 v111, v111
	v_exp_f32_e32 v112, v112
	v_mul_f32_e32 v110, v110, v111
	v_mul_f32_e32 v113, v113, v112
	v_sub_f32_e32 v111, 1.0, v111
	v_lshlrev_b32_e32 v112, 16, v137
	global_load_ushort v137, v29, s[38:39]
	v_mul_f32_e32 v111, v111, v113
	v_mul_f32_e32 v112, v110, v112
	v_cvt_pk_bf16_f32 v111, v111, s0
	v_cvt_pk_bf16_f32 v112, v112, s0
	ds_write_b16 v165, v112
	ds_write_b16 v166, v111
	v_mul_f32_e32 v111, 0x3fb8aa3b, v138
	v_mul_f32_e32 v112, 0xbfb8aa3b, v138
	global_load_dword v138, v30, s[54:55]
	v_exp_f32_e32 v111, v111
	v_exp_f32_e32 v112, v112
	v_mul_f32_e32 v110, v110, v111
	v_mul_f32_e32 v113, v113, v112
	v_sub_f32_e32 v111, 1.0, v111
	v_lshlrev_b32_e32 v112, 16, v139
	global_load_ushort v139, v31, s[38:39]
	v_mul_f32_e32 v111, v111, v113
	v_mul_f32_e32 v112, v110, v112
	v_cvt_pk_bf16_f32 v111, v111, s0
	v_cvt_pk_bf16_f32 v112, v112, s0
	ds_write_b16 v167, v112
	ds_write_b16 v168, v111
	v_mul_f32_e32 v111, 0x3fb8aa3b, v140
	v_mul_f32_e32 v112, 0xbfb8aa3b, v140
	global_load_dword v140, v32, s[54:55]
	v_exp_f32_e32 v111, v111
	v_exp_f32_e32 v112, v112
	v_mul_f32_e32 v110, v110, v111
	v_mul_f32_e32 v113, v113, v112
	v_sub_f32_e32 v111, 1.0, v111
	v_lshlrev_b32_e32 v112, 16, v141
	global_load_ushort v141, v33, s[38:39]
	v_mul_f32_e32 v111, v111, v113
	v_mul_f32_e32 v112, v110, v112
	v_cvt_pk_bf16_f32 v111, v111, s0
	v_cvt_pk_bf16_f32 v112, v112, s0
	ds_write_b16 v169, v112
	ds_write_b16 v170, v111
	v_mul_f32_e32 v111, 0x3fb8aa3b, v142
	v_mul_f32_e32 v112, 0xbfb8aa3b, v142
	global_load_dword v142, v34, s[54:55]
	v_exp_f32_e32 v111, v111
	v_exp_f32_e32 v112, v112
	v_mul_f32_e32 v110, v110, v111
	v_mul_f32_e32 v113, v113, v112
	v_sub_f32_e32 v111, 1.0, v111
	v_lshlrev_b32_e32 v112, 16, v143
	global_load_ushort v143, v35, s[38:39]
	v_mul_f32_e32 v111, v111, v113
	v_mul_f32_e32 v112, v110, v112
; __device__ __forceinline__ bf16_t f2bf(float x) { return (bf16_t)(cvt_pk_bf16(x, x) & 0xffffu); }
; __device__ __forceinline__ float bf2f(bf16_t v) { return __uint_as_float((unsigned)v << 16); }
; template <int DK, int DVS, bool RET> ...
;     ...
;                 for (int i = 0; i < PPT; ++i) { const int p = pg * PPT + i;
;                     const float qf = bf2f(qr[i]), kf = 1.f - __expf(lc[i]); bb += lc[i];
;                     QD[p * LK + kx] = f2bf(qf * __expf(bb)); KD[p * LK + kx] = f2bf(kf * __expf(-bb)); }
;             }
;             if (pg == 0) EL[kx] = __expf(bl);
	v_cvt_pk_bf16_f32 v111, v111, s0
	v_cvt_pk_bf16_f32 v112, v112, s0
	ds_write_b16 v171, v112
	ds_write_b16 v172, v111
	v_mul_f32_e32 v111, 0x3fb8aa3b, v147
	v_mul_f32_e32 v112, 0xbfb8aa3b, v147
	global_load_dword v147, v36, s[54:55]
	v_exp_f32_e32 v111, v111
	v_exp_f32_e32 v112, v112
	v_mul_f32_e32 v110, v110, v111
	v_mul_f32_e32 v113, v113, v112
	v_sub_f32_e32 v111, 1.0, v111
	v_lshlrev_b32_e32 v112, 16, v150
	global_load_ushort v150, v37, s[38:39]
	v_mul_f32_e32 v111, v111, v113
	v_mul_f32_e32 v112, v110, v112
	v_cvt_pk_bf16_f32 v111, v111, s0
	v_cvt_pk_bf16_f32 v112, v112, s0
	ds_write_b16 v173, v112
	ds_write_b16 v174, v111
	v_mul_f32_e32 v111, 0x3fb8aa3b, v151
	v_mul_f32_e32 v112, 0xbfb8aa3b, v151
	global_load_dword v151, v38, s[54:55]
	v_exp_f32_e32 v111, v111
	v_exp_f32_e32 v112, v112
	v_mul_f32_e32 v110, v110, v111
	v_mul_f32_e32 v113, v113, v112
	v_sub_f32_e32 v111, 1.0, v111
	v_lshlrev_b32_e32 v112, 16, v162
	global_load_ushort v162, v39, s[38:39]
	v_mul_f32_e32 v111, v111, v113
	v_mul_f32_e32 v112, v110, v112
	v_cvt_pk_bf16_f32 v111, v111, s0
	v_cvt_pk_bf16_f32 v112, v112, s0
	ds_write_b16 v175, v112
	ds_write_b16 v176, v111
	v_mul_f32_e32 v111, 0x3fb8aa3b, v210
	v_mul_f32_e32 v112, 0xbfb8aa3b, v210
	global_load_dword v210, v40, s[54:55]
	v_exp_f32_e32 v111, v111
	v_exp_f32_e32 v112, v112
	v_mul_f32_e32 v110, v110, v111
	v_mul_f32_e32 v113, v113, v112
	v_sub_f32_e32 v111, 1.0, v111
	v_lshlrev_b32_e32 v112, 16, v217
	global_load_ushort v217, v41, s[38:39]
	v_mul_f32_e32 v111, v111, v113
	v_mul_f32_e32 v112, v110, v112
	v_cvt_pk_bf16_f32 v111, v111, s0
	v_cvt_pk_bf16_f32 v112, v112, s0
	ds_write_b16 v177, v112
	ds_write_b16 v178, v111
	v_mul_f32_e32 v111, 0x3fb8aa3b, v220
	v_mul_f32_e32 v112, 0xbfb8aa3b, v220
	global_load_dword v220, v42, s[54:55]
	v_exp_f32_e32 v111, v111
	v_exp_f32_e32 v112, v112
	v_mul_f32_e32 v110, v110, v111
	v_mul_f32_e32 v113, v113, v112
	v_sub_f32_e32 v111, 1.0, v111
	v_lshlrev_b32_e32 v112, 16, v221
	global_load_ushort v221, v43, s[38:39]
	v_mul_f32_e32 v111, v111, v113
	v_mul_f32_e32 v112, v110, v112
	v_cvt_pk_bf16_f32 v111, v111, s0
	v_cvt_pk_bf16_f32 v112, v112, s0
	ds_write_b16 v179, v112
	ds_write_b16 v180, v111
	v_mul_f32_e32 v111, 0x3fb8aa3b, v222
	v_mul_f32_e32 v112, 0xbfb8aa3b, v222
	global_load_dword v222, v44, s[54:55]
	v_exp_f32_e32 v111, v111
	v_exp_f32_e32 v112, v112
	v_mul_f32_e32 v110, v110, v111
	v_mul_f32_e32 v113, v113, v112
	v_sub_f32_e32 v111, 1.0, v111
	v_lshlrev_b32_e32 v112, 16, v223
	global_load_ushort v223, v45, s[38:39]
	v_mul_f32_e32 v111, v111, v113
	v_mul_f32_e32 v112, v110, v112
	v_cvt_pk_bf16_f32 v111, v111, s0
	v_cvt_pk_bf16_f32 v112, v112, s0
	ds_write_b16 v181, v112
	ds_write_b16 v182, v111
	v_mul_f32_e32 v111, 0x3fb8aa3b, v224
	v_mul_f32_e32 v112, 0xbfb8aa3b, v224
	global_load_dword v224, v46, s[54:55]
	v_exp_f32_e32 v111, v111
	v_exp_f32_e32 v112, v112
	v_mul_f32_e32 v110, v110, v111
	v_mul_f32_e32 v113, v113, v112
	v_sub_f32_e32 v111, 1.0, v111
	v_lshlrev_b32_e32 v112, 16, v225
	global_load_ushort v225, v47, s[38:39]
	v_mul_f32_e32 v111, v111, v113
	v_mul_f32_e32 v112, v110, v112
	v_cvt_pk_bf16_f32 v111, v111, s0
	v_cvt_pk_bf16_f32 v112, v112, s0
	ds_write_b16 v183, v112
	ds_write_b16 v184, v111
	v_mul_f32_e32 v111, 0x3fb8aa3b, v226
	v_mul_f32_e32 v112, 0xbfb8aa3b, v226
	global_load_dword v226, v48, s[54:55]
	v_exp_f32_e32 v111, v111
	v_exp_f32_e32 v112, v112
	v_mul_f32_e32 v110, v110, v111
	v_mul_f32_e32 v113, v113, v112
	v_sub_f32_e32 v111, 1.0, v111
	v_lshlrev_b32_e32 v112, 16, v227
	global_load_ushort v227, v49, s[38:39]
	v_mul_f32_e32 v111, v111, v113
	v_mul_f32_e32 v112, v110, v112
	v_cvt_pk_bf16_f32 v111, v111, s0
	v_cvt_pk_bf16_f32 v112, v112, s0
	ds_write_b16 v185, v112
	ds_write_b16 v199, v111
	v_mul_f32_e32 v111, 0x3fb8aa3b, v228
	v_mul_f32_e32 v112, 0xbfb8aa3b, v228
	global_load_dword v228, v50, s[54:55]
	v_exp_f32_e32 v111, v111
	v_exp_f32_e32 v112, v112
	v_mul_f32_e32 v110, v110, v111
	v_mul_f32_e32 v113, v113, v112
	v_sub_f32_e32 v111, 1.0, v111
	v_lshlrev_b32_e32 v112, 16, v229
	global_load_ushort v229, v51, s[38:39]
	v_mul_f32_e32 v111, v111, v113
	v_mul_f32_e32 v112, v110, v112
	v_cvt_pk_bf16_f32 v111, v111, s0
	v_cvt_pk_bf16_f32 v112, v112, s0
	ds_write_b16 v200, v112
	ds_write_b16 v201, v111
	v_mul_f32_e32 v111, 0x3fb8aa3b, v230
	v_mul_f32_e32 v112, 0xbfb8aa3b, v230
	global_load_dword v230, v52, s[54:55]
	v_exp_f32_e32 v111, v111
	v_exp_f32_e32 v112, v112
	v_mul_f32_e32 v110, v110, v111
	v_mul_f32_e32 v113, v113, v112
	v_sub_f32_e32 v111, 1.0, v111
	v_lshlrev_b32_e32 v112, 16, v231
	global_load_ushort v231, v53, s[38:39]
	v_mul_f32_e32 v111, v111, v113
	v_mul_f32_e32 v112, v110, v112
	v_cvt_pk_bf16_f32 v111, v111, s0
	v_cvt_pk_bf16_f32 v112, v112, s0
	ds_write_b16 v202, v112
	ds_write_b16 v203, v111
	v_mul_f32_e32 v111, 0x3fb8aa3b, v232
	v_mul_f32_e32 v112, 0xbfb8aa3b, v232
	global_load_dword v232, v54, s[54:55]
	v_exp_f32_e32 v111, v111
	v_exp_f32_e32 v112, v112
	v_mul_f32_e32 v110, v110, v111
	v_mul_f32_e32 v113, v113, v112
	v_sub_f32_e32 v111, 1.0, v111
	v_lshlrev_b32_e32 v112, 16, v233
	global_load_ushort v233, v55, s[38:39]
	v_mul_f32_e32 v111, v111, v113
	v_mul_f32_e32 v112, v110, v112
	v_cvt_pk_bf16_f32 v111, v111, s0
	v_cvt_pk_bf16_f32 v112, v112, s0
	ds_write_b16 v204, v112
	ds_write_b16 v205, v111
	s_and_saveexec_b64 s[46:47], vcc
	s_cbranch_execz .LBB0_56
	v_add_f32_e32 v72, v72, v73
	v_add_f32_e32 v72, v72, v74
	v_add_f32_e32 v72, v72, v75
	v_mul_f32_e32 v72, 0x3fb8aa3b, v72
	v_exp_f32_e32 v72, v72
	ds_write_b32 v154, v72
